# placement: one 4-byte pad at the LN-mix phase entry (ph6 and every later phase 4 bytes further down), on the router rewrite
# speedup vs baseline: 1.0015x; 1.0015x over previous
.LBB0_662:
	s_nop 0
	v_readlane_b32 s0, v255, 4
	s_cmp_lt_i32 s0, 7
	s_cselect_b64 s[0:1], -1, 0
	s_cmp_gt_i32 s46, 6
	s_cselect_b64 s[2:3], -1, 0
	s_and_b64 s[0:1], s[0:1], s[2:3]
	s_andn2_b64 vcc, exec, s[0:1]
	v_mov_b32_e32 v4, s46
	v_lshrrev_b32_e32 v188, 8, v180
	s_cbranch_vccnz .LBB0_744
	v_readlane_b32 s0, v255, 2
	v_readlane_b32 s1, v255, 3
	s_load_dwordx2 s[0:1], s[0:1], 0x98
	v_sub_u32_e32 v0, 14, v188
	v_lshrrev_b32_e32 v0, 1, v0
	v_add_u32_e32 v4, 1, v0
	v_add_u32_e32 v181, 0x100, v180
	v_and_b32_e32 v5, 12, v4
	s_mov_b64 s[2:3], 0
	v_mov_b32_e32 v3, 0
	v_mov_b64_e32 v[0:1], v[180:181]
	s_waitcnt lgkmcnt(0)
	s_barrier
